# v028: v027 + transpose loop row-scale values fetched one tile ahead after the tile loads (two scale sets by parity) so the top wait covers only loads issued a full iteration earlier
# speedup vs baseline: 1.0010x; 1.0010x over previous
.LBB0_778:
.Lpro_g_skip:
	s_add_i32 s25, s25, s70
	s_cmpk_gt_i32 s25, 0x167f
	s_cselect_b64 s[10:11], -1, 0
	s_and_b64 vcc, exec, s[10:11]
	s_cbranch_vccnz .Lpro_nonext
	s_mul_hi_i32 s0, s25, 0xb60b60b7
	s_add_i32 s0, s0, s25
	s_lshr_b32 s1, s0, 31
	s_ashr_i32 s0, s0, 11
	s_add_i32 s20, s0, s1
	s_mul_i32 s0, s20, 0xfffff4c0
	s_add_i32 s9, s25, s0
	s_cmpk_lt_i32 s9, 0x400
	s_cselect_b64 s[18:19], -1, 0
	s_cmpk_gt_i32 s9, 0x3ff
	s_mov_b64 s[22:23], -1
	s_cbranch_scc0 .LBB0_807
	s_cmpk_gt_u32 s9, 0x4bf
	s_cbranch_scc0 .LBB0_804
	s_cmpk_gt_u32 s9, 0x73f
	s_cbranch_scc0 .LBB0_786
	s_mul_i32 s0, s20, 0xb40
	s_ashr_i32 s21, s20, 31
	s_sub_i32 s49, s25, s0
	s_lshl_b64 s[14:15], s[20:21], 22
	s_cmpk_gt_u32 s9, 0x93f
	s_cbranch_scc0 .LBB0_784
	s_add_i32 s51, s49, 0xfffff6c0
	s_lshl_b64 s[0:1], s[14:15], 2
	v_readlane_b32 s52, v253, 8
	v_readlane_b32 s53, v253, 9
	s_add_u32 s0, s52, s0
	s_addc_u32 s1, s53, s1
	s_lshl_b64 s[12:13], s[14:15], 1
	s_add_u32 s12, s33, s12
	v_readlane_b32 s54, v253, 10
	v_readlane_b32 s55, v253, 11
	v_readlane_b32 s56, v253, 12
	v_readlane_b32 s57, v253, 13
	v_readlane_b32 s58, v253, 14
	v_readlane_b32 s59, v253, 15
	s_addc_u32 s13, s34, s13
	s_mov_b64 s[22:23], 0

.LBB0_831:
	s_cmpk_lt_u32 s25, 0x200
	s_cbranch_scc1 .Ltr_prime_done
	s_bitcmp1_b32 s25, 8
	s_cbranch_scc1 .Ltr_gA_t
	v_mov_b32_e32 v140, 1.0
	v_mov_b32_e32 v141, 1.0
	v_mov_b32_e32 v142, 1.0
	v_mov_b32_e32 v143, 1.0
	s_or_b32 s0, s17, s32
	s_cmp_eq_u32 s0, 0
	s_cbranch_scc1 .Ltr_wn_t
	s_mov_b32 s0, s17
	s_mov_b32 s1, s32
	v_add_u32_e32 v48, s98, v34
	v_ashrrev_i32_e32 v49, 31, v48
	v_lshl_add_u64 v[48:49], v[48:49], 2, s[0:1]
	global_load_dword v140, v[48:49], off
	global_load_dword v141, v[48:49], off offset:64
	global_load_dword v142, v[48:49], off offset:128
	global_load_dword v143, v[48:49], off offset:192
	s_branch .Ltr_wg_t
.Ltr_gA_t:
	v_mov_b32_e32 v118, 1.0
	v_mov_b32_e32 v119, 1.0
	v_mov_b32_e32 v120, 1.0
	v_mov_b32_e32 v121, 1.0
	s_or_b32 s0, s17, s32
	s_cmp_eq_u32 s0, 0
	s_cbranch_scc1 .Ltr_wn_t
	s_mov_b32 s0, s17
	s_mov_b32 s1, s32
	v_add_u32_e32 v48, s98, v34
	v_ashrrev_i32_e32 v49, 31, v48
	v_lshl_add_u64 v[48:49], v[48:49], 2, s[0:1]
	global_load_dword v118, v[48:49], off
	global_load_dword v119, v[48:49], off offset:64
	global_load_dword v120, v[48:49], off offset:128
	global_load_dword v121, v[48:49], off offset:192
.Ltr_wg_t:
	s_waitcnt vmcnt(8)
	s_branch .Lpro_body

.Ltr_prime_done:
	v_mov_b32_e32 v118, 1.0
	v_mov_b32_e32 v119, 1.0
	v_mov_b32_e32 v120, 1.0
	v_mov_b32_e32 v121, 1.0
	s_cmp_eq_u64 s[6:7], 0
	s_cbranch_scc1 .Ltr_pg_skip
	v_add_u32_e32 v48, s8, v34
	v_ashrrev_i32_e32 v49, 31, v48
	v_lshl_add_u64 v[48:49], v[48:49], 2, s[6:7]
	global_load_dword v118, v[48:49], off
	global_load_dword v119, v[48:49], off offset:64
	global_load_dword v120, v[48:49], off offset:128
	global_load_dword v121, v[48:49], off offset:192

.Lpro_body:
	s_bitcmp1_b32 s25, 8
	s_cbranch_scc1 .Ltr_gcB
	v_mov_b32_e32 v46, v118
	v_mov_b32_e32 v47, v119
	v_mov_b32_e32 v52, v120
	v_mov_b32_e32 v53, v121
	s_branch .Ltr_gcd
.Ltr_gcB:
	v_mov_b32_e32 v46, v140
	v_mov_b32_e32 v47, v141
	v_mov_b32_e32 v52, v142
	v_mov_b32_e32 v53, v143
